# pitch-160 + sel-loop two-ahead cache-warming loads + paired importance LDS read-modify-writes
# speedup vs baseline: 1.0040x; 1.0040x over previous
; #define SL_GLOAD(SK, SV, j_) do { SK = *(const v4u*)(ksb + (size_t)((j_) * 64 + srow) * U2_LD + sch); SV = *(const v4u*)(vsb + (size_t)srow * SEQ + (j_) * 64 + sch); } while (0)
; #define SL_LWRITE(SK, SV, buf_) do { LAS unsigned char* nb_ = lds + NSA_TILE0 + (buf_) * NSA_TILE_STRIDE; *(LAS v4u*)((LAS bf16*)nb_ + krow * KT_LD + sch) = SK; *(LAS v4u*)((LAS bf16*)(nb_ + NSA_V_OFF) + srow * KT_LD + sch) = SV; } while (0)
; __device__ __forceinline__ int pop_bit(u64& u0, u64& u1, u64& u2, u64& u3) {
;     if (u0) { const int j = __builtin_ctzll(u0); u0 &= u0 - 1; return j; }
;     if (u1) { const int j = __builtin_ctzll(u1); u1 &= u1 - 1; return 64 + j; }
;     if (u2) { const int j = __builtin_ctzll(u2); u2 &= u2 - 1; return 128 + j; }
;     if (u3) { const int j = __builtin_ctzll(u3); u3 &= u3 - 1; return 192 + j; }
;     return -1;
; }
; __device__ __forceinline__ void nsa_block(LAS unsigned char* lds, int b, int g, int t0b, int tid) {
;     ...
;         while (jc >= 0) {
;             const int jn = pop_bit(u0, u1, u2, u3);
;             if (jn >= 0) SL_GLOAD(skA, svA, jn);
;             SL_COMPUTE(jc, sidx & 1);
;             if (jn >= 0) SL_LWRITE(skA, svA, (sidx + 1) & 1);
.LBB0_1037:
	s_cmp_gt_i32 s60, -1
	s_cselect_b64 s[54:55], -1, 0
	s_cmp_lt_i32 s60, 0
	s_cselect_b64 s[36:37], -1, 0
	s_and_b64 vcc, exec, s[36:37]
	s_cbranch_vccnz .LBB0_1039
	s_waitcnt vmcnt(2)
	v_lshl_add_u32 v16, s60, 6, v88
	s_lshl_b32 s20, s60, 7
	v_mad_i64_i32 v[16:17], s[10:11], v16, s79, v[166:167]
	s_waitcnt vmcnt(2)
	v_lshl_add_u64 v[20:21], v[168:169], 0, s[20:21]
	global_load_dwordx4 v[16:19], v[16:17], off
	s_nop 0
	global_load_dwordx4 v[20:23], v[20:21], off
	s_mov_b32 s98, s60
	s_cmp_eq_u64 s[46:47], 0
	s_cbranch_scc1 .Lselpk_a
	s_ff1_i32_b64 s98, s[46:47]
	s_or_b32 s98, s98, 0xc0
.Lselpk_a:
	s_cmp_eq_u64 s[48:49], 0
	s_cbranch_scc1 .Lselpk_b
	s_ff1_i32_b64 s98, s[48:49]
	s_or_b32 s98, s98, 0x80
.Lselpk_b:
	s_cmp_eq_u64 s[50:51], 0
	s_cbranch_scc1 .Lselpk_c
	s_ff1_i32_b64 s98, s[50:51]
	s_or_b32 s98, s98, 64
.Lselpk_c:
	s_cmp_eq_u64 s[52:53], 0
	s_cbranch_scc1 .Lselpk_d
	s_ff1_i32_b64 s98, s[52:53]
.Lselpk_d:
	s_waitcnt vmcnt(2)
	v_lshl_add_u32 v250, s98, 6, v88
	s_lshl_b32 s100, s98, 7
	s_mov_b32 s101, 0
	v_mad_i64_i32 v[250:251], s[10:11], v250, s79, v[166:167]
	v_lshl_add_u64 v[252:253], v[168:169], 0, s[100:101]
	global_load_dword v250, v[250:251], off
	global_load_dword v252, v[252:253], off

; #define SL_GLOAD(SK, SV, j_) do { SK = *(const v4u*)(ksb + (size_t)((j_) * 64 + srow) * U2_LD + sch); SV = *(const v4u*)(vsb + (size_t)srow * SEQ + (j_) * 64 + sch); } while (0)
; #define SL_LWRITE(SK, SV, buf_) do { LAS unsigned char* nb_ = lds + NSA_TILE0 + (buf_) * NSA_TILE_STRIDE; *(LAS v4u*)((LAS bf16*)nb_ + krow * KT_LD + sch) = SK; *(LAS v4u*)((LAS bf16*)(nb_ + NSA_V_OFF) + srow * KT_LD + sch) = SV; } while (0)
; __device__ __forceinline__ void nsa_block(LAS unsigned char* lds, int b, int g, int t0b, int tid) {
;     ...
;             if (jn >= 0) SL_GLOAD(skA, svA, jn);
;             SL_COMPUTE(jc, sidx & 1);
;             if (jn >= 0) SL_LWRITE(skA, svA, (sidx + 1) & 1);
.LBB0_1045:
	s_andn2_b32 s10, 1, s43
	s_mulk_i32 s10, 0x5000
	s_add_i32 s10, s10, 0
	s_add_i32 s10, s10, 0x10800
	v_add3_u32 v165, s10, v221, v92
	s_waitcnt vmcnt(3)
	ds_write_b128 v165, v[16:19]
	v_add3_u32 v165, s10, v222, v92
	s_waitcnt vmcnt(2)
	ds_write_b128 v165, v[20:23] offset:10240
